# seams: non-leader workgroups sleep ~0.3us before their first poll of the cross-XCC counter
# speedup vs baseline: 1.0032x; 1.0032x over previous
; __device__ __forceinline__ unsigned xb_ld(unsigned* p)              { return __hip_atomic_load(p, __ATOMIC_RELAXED, __HIP_MEMORY_SCOPE_AGENT); }
; __device__ __forceinline__ unsigned xb_add(unsigned* p, unsigned v) { return __hip_atomic_fetch_add(p, v, __ATOMIC_RELAXED, __HIP_MEMORY_SCOPE_AGENT); }
; #define XB_SPIN(cond, bar) do { unsigned _sp = 0; while (cond) { __builtin_amdgcn_s_sleep(1); \
;     if ((++_sp & 255u) == 0u) { if (xb_ld(&(bar)[XB_TMO])) break; if (_sp > XB_SPIN_CAP) { atomicAdd(&(bar)[XB_TMO], 1u); break; } } } } while (0)
; __device__ __forceinline__ void xcd_barrier(const XcdBarrier& b) {
;     asm volatile("s_waitcnt vmcnt(0)" ::: "memory");
;     __syncthreads();
;     if (threadIdx.x == 0) {
;         unsigned* bar = b.bar;
;         __builtin_amdgcn_s_waitcnt(0);
;         unsigned nloc = b.st[0], nx = b.st[1];
;         if (nloc == 0u) { xcd_barrier_complete(bar, b.x, nloc, nx); b.st[0] = nloc; b.st[1] = nx; }
;         const unsigned old = xb_add(&bar[XB_XSUB(b.x)], 1u);
;         const unsigned gen = old / nloc;
;         if (old + 1u == (gen + 1u) * nloc) {
;             __builtin_amdgcn_fence(__ATOMIC_RELEASE, "agent");
;             asm volatile("s_waitcnt vmcnt(0)" ::: "memory");
;             const unsigned og = xb_add(&bar[XB_TOP], 1u);
;             const unsigned tg = og / nx;
;             if (og + 1u == (tg + 1u) * nx) xb_add(&bar[XB_TOPGEN], 1u);
;             else XB_SPIN(xb_ld(&bar[XB_TOPGEN]) == tg, bar);
.LBB0_144:
	s_cmp_lt_i32 s56, 2
	s_cselect_b64 s[10:11], -1, 0
	s_cmp_gt_i32 s57, 1
	s_cselect_b64 s[0:1], -1, 0
	s_and_b64 s[0:1], s[10:11], s[0:1]
	s_andn2_b64 vcc, exec, s[0:1]
	s_cbranch_vccnz .LBB0_443
	s_andn2_b64 vcc, exec, s[4:5]
	s_cbranch_vccnz .LBB0_199
	s_getreg_b32 s3, hwreg(HW_REG_XCC_ID, 0, 4)
	s_waitcnt vmcnt(0)
	v_cmp_eq_u32_e32 vcc, 0, v178
	s_waitcnt lgkmcnt(0)
	s_barrier
	s_and_saveexec_b64 s[0:1], vcc
	s_cbranch_execz .LBB0_198
	buffer_inv sc1
	v_mov_b32_e32 v0, 0x23ff0
	ds_read2_b32 v[0:1], v0 offset1:1
	s_and_b32 s98, s3, 15
	s_lshl_b32 s98, s98, 8
	s_add_u32 s98, s54, s98
	s_addc_u32 s99, s55, 0
	s_add_u32 s98, s98, 0x22a3400
	s_addc_u32 s99, s99, 0
	v_mov_b32_e32 v2, 0
	v_mov_b32_e32 v3, 1
	global_atomic_add v4, v2, v3, s[98:99] sc0
	s_add_u32 s100, s54, 0x22a5400
	s_addc_u32 s101, s55, 0
	s_waitcnt vmcnt(0) lgkmcnt(0)
	v_mul_u32_u24_e32 v0, 1, v0
	v_mul_u32_u24_e32 v1, 1, v1
	v_add_u32_e32 v4, 1, v4
	v_cmp_eq_u32_e32 vcc, v4, v0
	s_cbranch_vccz .Lxb_nl_s0
	buffer_wbl2 sc1
	s_waitcnt vmcnt(0)
	global_atomic_add v2, v3, s[100:101]
	s_branch .Lxb_poll_s0
.Lxb_nl_s0:
	s_sleep 12

; __device__ __forceinline__ unsigned xb_ld(unsigned* p)              { return __hip_atomic_load(p, __ATOMIC_RELAXED, __HIP_MEMORY_SCOPE_AGENT); }
; __device__ __forceinline__ unsigned xb_add(unsigned* p, unsigned v) { return __hip_atomic_fetch_add(p, v, __ATOMIC_RELAXED, __HIP_MEMORY_SCOPE_AGENT); }
; #define XB_SPIN(cond, bar) do { unsigned _sp = 0; while (cond) { __builtin_amdgcn_s_sleep(1); \
;     if ((++_sp & 255u) == 0u) { if (xb_ld(&(bar)[XB_TMO])) break; if (_sp > XB_SPIN_CAP) { atomicAdd(&(bar)[XB_TMO], 1u); break; } } } } while (0)
; __device__ __forceinline__ void xcd_barrier(const XcdBarrier& b) {
;     asm volatile("s_waitcnt vmcnt(0)" ::: "memory");
;     __syncthreads();
;     if (threadIdx.x == 0) {
;         unsigned* bar = b.bar;
;         __builtin_amdgcn_s_waitcnt(0);
;         unsigned nloc = b.st[0], nx = b.st[1];
;         if (nloc == 0u) { xcd_barrier_complete(bar, b.x, nloc, nx); b.st[0] = nloc; b.st[1] = nx; }
;         const unsigned old = xb_add(&bar[XB_XSUB(b.x)], 1u);
;         const unsigned gen = old / nloc;
;         if (old + 1u == (gen + 1u) * nloc) {
;             __builtin_amdgcn_fence(__ATOMIC_RELEASE, "agent");
;             asm volatile("s_waitcnt vmcnt(0)" ::: "memory");
;             const unsigned og = xb_add(&bar[XB_TOP], 1u);
;             const unsigned tg = og / nx;
;             if (og + 1u == (tg + 1u) * nx) xb_add(&bar[XB_TOPGEN], 1u);
;             else XB_SPIN(xb_ld(&bar[XB_TOPGEN]) == tg, bar);
.LBB0_443:
	s_cmp_lt_i32 s56, 3
	s_waitcnt lgkmcnt(0)
	s_cselect_b64 s[14:15], -1, 0
	s_cmp_gt_i32 s57, 2
	s_cselect_b64 s[0:1], -1, 0
	s_and_b64 s[0:1], s[14:15], s[0:1]
	s_andn2_b64 vcc, exec, s[0:1]
	s_cbranch_vccnz .LBB0_545
	s_and_b64 vcc, exec, s[10:11]
	s_cbranch_vccz .LBB0_498
	s_getreg_b32 s3, hwreg(HW_REG_XCC_ID, 0, 4)
	s_waitcnt vmcnt(0)
	v_cmp_eq_u32_e32 vcc, 0, v178
	s_waitcnt vmcnt(0)
	s_barrier
	s_and_saveexec_b64 s[0:1], vcc
	s_cbranch_execz .LBB0_497
	buffer_inv sc1
	v_mov_b32_e32 v0, 0x23ff0
	ds_read2_b32 v[0:1], v0 offset1:1
	s_and_b32 s98, s3, 15
	s_lshl_b32 s98, s98, 8
	s_add_u32 s98, s54, s98
	s_addc_u32 s99, s55, 0
	s_add_u32 s98, s98, 0x22a3400
	s_addc_u32 s99, s99, 0
	v_mov_b32_e32 v2, 0
	v_mov_b32_e32 v3, 1
	global_atomic_add v4, v2, v3, s[98:99] sc0
	s_add_u32 s100, s54, 0x22a5400
	s_addc_u32 s101, s55, 0
	s_waitcnt vmcnt(0) lgkmcnt(0)
	v_mul_u32_u24_e32 v0, 2, v0
	v_mul_u32_u24_e32 v1, 2, v1
	v_add_u32_e32 v4, 1, v4
	v_cmp_eq_u32_e32 vcc, v4, v0
	s_cbranch_vccz .Lxb_nl_s1
	buffer_wbl2 sc1
	s_waitcnt vmcnt(0)
	global_atomic_add v2, v3, s[100:101]
	s_branch .Lxb_poll_s1

; __device__ __forceinline__ unsigned xb_ld(unsigned* p)              { return __hip_atomic_load(p, __ATOMIC_RELAXED, __HIP_MEMORY_SCOPE_AGENT); }
; __device__ __forceinline__ unsigned xb_add(unsigned* p, unsigned v) { return __hip_atomic_fetch_add(p, v, __ATOMIC_RELAXED, __HIP_MEMORY_SCOPE_AGENT); }
; #define XB_SPIN(cond, bar) do { unsigned _sp = 0; while (cond) { __builtin_amdgcn_s_sleep(1); \
;     if ((++_sp & 255u) == 0u) { if (xb_ld(&(bar)[XB_TMO])) break; if (_sp > XB_SPIN_CAP) { atomicAdd(&(bar)[XB_TMO], 1u); break; } } } } while (0)
; __device__ __forceinline__ void xcd_barrier(const XcdBarrier& b) {
;     asm volatile("s_waitcnt vmcnt(0)" ::: "memory");
;     __syncthreads();
;     if (threadIdx.x == 0) {
;         unsigned* bar = b.bar;
;         __builtin_amdgcn_s_waitcnt(0);
;         unsigned nloc = b.st[0], nx = b.st[1];
;         if (nloc == 0u) { xcd_barrier_complete(bar, b.x, nloc, nx); b.st[0] = nloc; b.st[1] = nx; }
;         const unsigned old = xb_add(&bar[XB_XSUB(b.x)], 1u);
;         const unsigned gen = old / nloc;
;         if (old + 1u == (gen + 1u) * nloc) {
;             __builtin_amdgcn_fence(__ATOMIC_RELEASE, "agent");
;             asm volatile("s_waitcnt vmcnt(0)" ::: "memory");
;             const unsigned og = xb_add(&bar[XB_TOP], 1u);
;             const unsigned tg = og / nx;
;             if (og + 1u == (tg + 1u) * nx) xb_add(&bar[XB_TOPGEN], 1u);
;             else XB_SPIN(xb_ld(&bar[XB_TOPGEN]) == tg, bar);
.LBB0_545:
	s_cmp_lt_i32 s56, 4
	s_cselect_b64 s[0:1], -1, 0
	s_cmp_gt_i32 s57, 3
	s_cselect_b64 s[4:5], -1, 0
	s_and_b64 s[4:5], s[0:1], s[4:5]
	s_andn2_b64 vcc, exec, s[4:5]
	s_cbranch_vccnz .LBB0_670
	s_andn2_b64 vcc, exec, s[14:15]
	s_cbranch_vccnz .LBB0_558
	s_getreg_b32 s3, hwreg(HW_REG_XCC_ID, 0, 4)
	s_waitcnt vmcnt(0)
	v_cmp_eq_u32_e32 vcc, 0, v178
	s_waitcnt vmcnt(0)
	s_barrier
	s_and_saveexec_b64 s[4:5], vcc
	s_cbranch_execz .LBB0_631
	buffer_inv sc1
	v_mov_b32_e32 v0, 0x23ff0
	ds_read2_b32 v[0:1], v0 offset1:1
	s_and_b32 s98, s3, 15
	s_lshl_b32 s98, s98, 8
	s_add_u32 s98, s54, s98
	s_addc_u32 s99, s55, 0
	s_add_u32 s98, s98, 0x22a3400
	s_addc_u32 s99, s99, 0
	v_mov_b32_e32 v2, 0
	v_mov_b32_e32 v3, 1
	global_atomic_add v4, v2, v3, s[98:99] sc0
	s_add_u32 s100, s54, 0x22a5400
	s_addc_u32 s101, s55, 0
	s_waitcnt vmcnt(0) lgkmcnt(0)
	v_mul_u32_u24_e32 v0, 3, v0
	v_mul_u32_u24_e32 v1, 3, v1
	v_add_u32_e32 v4, 1, v4
	v_cmp_eq_u32_e32 vcc, v4, v0
	s_cbranch_vccz .Lxb_nl_s2
	buffer_wbl2 sc1
	s_waitcnt vmcnt(0)
	global_atomic_add v2, v3, s[100:101]
	s_branch .Lxb_poll_s2

; __device__ __forceinline__ unsigned xb_ld(unsigned* p)              { return __hip_atomic_load(p, __ATOMIC_RELAXED, __HIP_MEMORY_SCOPE_AGENT); }
; __device__ __forceinline__ unsigned xb_add(unsigned* p, unsigned v) { return __hip_atomic_fetch_add(p, v, __ATOMIC_RELAXED, __HIP_MEMORY_SCOPE_AGENT); }
; #define XB_SPIN(cond, bar) do { unsigned _sp = 0; while (cond) { __builtin_amdgcn_s_sleep(1); \
;     if ((++_sp & 255u) == 0u) { if (xb_ld(&(bar)[XB_TMO])) break; if (_sp > XB_SPIN_CAP) { atomicAdd(&(bar)[XB_TMO], 1u); break; } } } } while (0)
; __device__ __forceinline__ void xcd_barrier(const XcdBarrier& b) {
;     asm volatile("s_waitcnt vmcnt(0)" ::: "memory");
;     __syncthreads();
;     if (threadIdx.x == 0) {
;         unsigned* bar = b.bar;
;         __builtin_amdgcn_s_waitcnt(0);
;         unsigned nloc = b.st[0], nx = b.st[1];
;         if (nloc == 0u) { xcd_barrier_complete(bar, b.x, nloc, nx); b.st[0] = nloc; b.st[1] = nx; }
;         const unsigned old = xb_add(&bar[XB_XSUB(b.x)], 1u);
;         const unsigned gen = old / nloc;
;         if (old + 1u == (gen + 1u) * nloc) {
;             __builtin_amdgcn_fence(__ATOMIC_RELEASE, "agent");
;             asm volatile("s_waitcnt vmcnt(0)" ::: "memory");
;             const unsigned og = xb_add(&bar[XB_TOP], 1u);
;             const unsigned tg = og / nx;
;             if (og + 1u == (tg + 1u) * nx) xb_add(&bar[XB_TOPGEN], 1u);
;             else XB_SPIN(xb_ld(&bar[XB_TOPGEN]) == tg, bar);
.LBB0_670:
	s_cmp_lt_i32 s56, 5
	s_cselect_b64 s[14:15], -1, 0
	s_cmp_gt_i32 s57, 4
	s_cselect_b64 s[4:5], -1, 0
	s_and_b64 s[4:5], s[14:15], s[4:5]
	s_andn2_b64 vcc, exec, s[4:5]
	s_cbranch_vccnz .LBB0_745
	s_andn2_b64 vcc, exec, s[0:1]
	s_cbranch_vccnz .LBB0_725
	s_getreg_b32 s3, hwreg(HW_REG_XCC_ID, 0, 4)
	s_waitcnt vmcnt(0)
	v_cmp_eq_u32_e32 vcc, 0, v178
	s_waitcnt vmcnt(0)
	s_barrier
	s_and_saveexec_b64 s[0:1], vcc
	s_cbranch_execz .LBB0_724
	buffer_inv sc1
	v_mov_b32_e32 v0, 0x23ff0
	ds_read2_b32 v[0:1], v0 offset1:1
	s_and_b32 s98, s3, 15
	s_lshl_b32 s98, s98, 8
	s_add_u32 s98, s54, s98
	s_addc_u32 s99, s55, 0
	s_add_u32 s98, s98, 0x22a3400
	s_addc_u32 s99, s99, 0
	v_mov_b32_e32 v2, 0
	v_mov_b32_e32 v3, 1
	global_atomic_add v4, v2, v3, s[98:99] sc0
	s_add_u32 s100, s54, 0x22a5400
	s_addc_u32 s101, s55, 0
	s_waitcnt vmcnt(0) lgkmcnt(0)
	v_mul_u32_u24_e32 v0, 4, v0
	v_mul_u32_u24_e32 v1, 4, v1
	v_add_u32_e32 v4, 1, v4
	v_cmp_eq_u32_e32 vcc, v4, v0
	s_cbranch_vccz .Lxb_nl_s3
	buffer_wbl2 sc1
	s_waitcnt vmcnt(0)
	global_atomic_add v2, v3, s[100:101]
	s_branch .Lxb_poll_s3

; __device__ __forceinline__ unsigned xb_ld(unsigned* p)              { return __hip_atomic_load(p, __ATOMIC_RELAXED, __HIP_MEMORY_SCOPE_AGENT); }
; __device__ __forceinline__ unsigned xb_add(unsigned* p, unsigned v) { return __hip_atomic_fetch_add(p, v, __ATOMIC_RELAXED, __HIP_MEMORY_SCOPE_AGENT); }
; #define XB_SPIN(cond, bar) do { unsigned _sp = 0; while (cond) { __builtin_amdgcn_s_sleep(1); \
;     if ((++_sp & 255u) == 0u) { if (xb_ld(&(bar)[XB_TMO])) break; if (_sp > XB_SPIN_CAP) { atomicAdd(&(bar)[XB_TMO], 1u); break; } } } } while (0)
; __device__ __forceinline__ void xcd_barrier(const XcdBarrier& b) {
;     asm volatile("s_waitcnt vmcnt(0)" ::: "memory");
;     __syncthreads();
;     if (threadIdx.x == 0) {
;         unsigned* bar = b.bar;
;         __builtin_amdgcn_s_waitcnt(0);
;         unsigned nloc = b.st[0], nx = b.st[1];
;         if (nloc == 0u) { xcd_barrier_complete(bar, b.x, nloc, nx); b.st[0] = nloc; b.st[1] = nx; }
;         const unsigned old = xb_add(&bar[XB_XSUB(b.x)], 1u);
;         const unsigned gen = old / nloc;
;         if (old + 1u == (gen + 1u) * nloc) {
;             __builtin_amdgcn_fence(__ATOMIC_RELEASE, "agent");
;             asm volatile("s_waitcnt vmcnt(0)" ::: "memory");
;             const unsigned og = xb_add(&bar[XB_TOP], 1u);
;             const unsigned tg = og / nx;
;             if (og + 1u == (tg + 1u) * nx) xb_add(&bar[XB_TOPGEN], 1u);
;             else XB_SPIN(xb_ld(&bar[XB_TOPGEN]) == tg, bar);
.LBB0_745:
	s_cmp_lt_i32 s56, 6
	s_cselect_b64 s[0:1], -1, 0
	s_cmp_gt_i32 s57, 5
	s_cselect_b64 s[4:5], -1, 0
	s_and_b64 s[0:1], s[0:1], s[4:5]
	s_andn2_b64 vcc, exec, s[0:1]
	s_cbranch_vccnz .LBB0_841
	s_andn2_b64 vcc, exec, s[14:15]
	s_cbranch_vccnz .LBB0_800
	s_getreg_b32 s3, hwreg(HW_REG_XCC_ID, 0, 4)
	s_waitcnt vmcnt(0)
	v_cmp_eq_u32_e32 vcc, 0, v178
	s_waitcnt vmcnt(0)
	s_barrier
	s_and_saveexec_b64 s[0:1], vcc
	s_cbranch_execz .LBB0_799
	buffer_inv sc1
	v_mov_b32_e32 v0, 0x23ff0
	ds_read2_b32 v[0:1], v0 offset1:1
	s_and_b32 s98, s3, 15
	s_lshl_b32 s98, s98, 8
	s_add_u32 s98, s54, s98
	s_addc_u32 s99, s55, 0
	s_add_u32 s98, s98, 0x22a3400
	s_addc_u32 s99, s99, 0
	v_mov_b32_e32 v2, 0
	v_mov_b32_e32 v3, 1
	global_atomic_add v4, v2, v3, s[98:99] sc0
	s_add_u32 s100, s54, 0x22a5400
	s_addc_u32 s101, s55, 0
	s_waitcnt vmcnt(0) lgkmcnt(0)
	v_mul_u32_u24_e32 v0, 5, v0
	v_mul_u32_u24_e32 v1, 5, v1
	v_add_u32_e32 v4, 1, v4
	v_cmp_eq_u32_e32 vcc, v4, v0
	s_cbranch_vccz .Lxb_nl_s4
	buffer_wbl2 sc1
	s_waitcnt vmcnt(0)
	global_atomic_add v2, v3, s[100:101]
	s_branch .Lxb_poll_s4

; __device__ __forceinline__ unsigned xb_ld(unsigned* p)              { return __hip_atomic_load(p, __ATOMIC_RELAXED, __HIP_MEMORY_SCOPE_AGENT); }
; __device__ __forceinline__ unsigned xb_add(unsigned* p, unsigned v) { return __hip_atomic_fetch_add(p, v, __ATOMIC_RELAXED, __HIP_MEMORY_SCOPE_AGENT); }
; #define XB_SPIN(cond, bar) do { unsigned _sp = 0; while (cond) { __builtin_amdgcn_s_sleep(1); \
;     if ((++_sp & 255u) == 0u) { if (xb_ld(&(bar)[XB_TMO])) break; if (_sp > XB_SPIN_CAP) { atomicAdd(&(bar)[XB_TMO], 1u); break; } } } } while (0)
; __device__ __forceinline__ void xcd_barrier(const XcdBarrier& b) {
;     asm volatile("s_waitcnt vmcnt(0)" ::: "memory");
;     __syncthreads();
;     if (threadIdx.x == 0) {
;         unsigned* bar = b.bar;
;         __builtin_amdgcn_s_waitcnt(0);
;         unsigned nloc = b.st[0], nx = b.st[1];
;         if (nloc == 0u) { xcd_barrier_complete(bar, b.x, nloc, nx); b.st[0] = nloc; b.st[1] = nx; }
;         const unsigned old = xb_add(&bar[XB_XSUB(b.x)], 1u);
;         const unsigned gen = old / nloc;
;         if (old + 1u == (gen + 1u) * nloc) {
;             __builtin_amdgcn_fence(__ATOMIC_RELEASE, "agent");
;             asm volatile("s_waitcnt vmcnt(0)" ::: "memory");
;             const unsigned og = xb_add(&bar[XB_TOP], 1u);
;             const unsigned tg = og / nx;
;             if (og + 1u == (tg + 1u) * nx) xb_add(&bar[XB_TOPGEN], 1u);
;             else XB_SPIN(xb_ld(&bar[XB_TOPGEN]) == tg, bar);
.LBB0_841:
	s_cmp_lt_i32 s56, 8
	s_cselect_b64 s[6:7], -1, 0
	s_cmp_gt_i32 s57, 7
	s_cselect_b64 s[0:1], -1, 0
	s_and_b64 s[0:1], s[6:7], s[0:1]
	s_andn2_b64 vcc, exec, s[0:1]
	s_cbranch_vccnz .LBB0_934
	s_cmp_gt_i32 s56, 6
	s_cbranch_scc1 .LBB0_896
	s_getreg_b32 s3, hwreg(HW_REG_XCC_ID, 0, 4)
	s_waitcnt vmcnt(0)
	v_cmp_eq_u32_e32 vcc, 0, v178
	s_waitcnt vmcnt(0)
	s_barrier
	s_and_saveexec_b64 s[0:1], vcc
	s_cbranch_execz .LBB0_895
	buffer_inv sc1
	v_mov_b32_e32 v0, 0x23ff0
	ds_read2_b32 v[0:1], v0 offset1:1
	s_and_b32 s98, s3, 15
	s_lshl_b32 s98, s98, 8
	s_add_u32 s98, s54, s98
	s_addc_u32 s99, s55, 0
	s_add_u32 s98, s98, 0x22a3400
	s_addc_u32 s99, s99, 0
	v_mov_b32_e32 v2, 0
	v_mov_b32_e32 v3, 1
	global_atomic_add v4, v2, v3, s[98:99] sc0
	s_add_u32 s100, s54, 0x22a5400
	s_addc_u32 s101, s55, 0
	s_waitcnt vmcnt(0) lgkmcnt(0)
	v_mul_u32_u24_e32 v0, 6, v0
	v_mul_u32_u24_e32 v1, 6, v1
	v_add_u32_e32 v4, 1, v4
	v_cmp_eq_u32_e32 vcc, v4, v0
	s_cbranch_vccz .Lxb_nl_s5
	buffer_wbl2 sc1
	s_waitcnt vmcnt(0)
	global_atomic_add v2, v3, s[100:101]
	s_branch .Lxb_poll_s5

; __device__ __forceinline__ unsigned xb_ld(unsigned* p)              { return __hip_atomic_load(p, __ATOMIC_RELAXED, __HIP_MEMORY_SCOPE_AGENT); }
; __device__ __forceinline__ unsigned xb_add(unsigned* p, unsigned v) { return __hip_atomic_fetch_add(p, v, __ATOMIC_RELAXED, __HIP_MEMORY_SCOPE_AGENT); }
; #define XB_SPIN(cond, bar) do { unsigned _sp = 0; while (cond) { __builtin_amdgcn_s_sleep(1); \
;     if ((++_sp & 255u) == 0u) { if (xb_ld(&(bar)[XB_TMO])) break; if (_sp > XB_SPIN_CAP) { atomicAdd(&(bar)[XB_TMO], 1u); break; } } } } while (0)
; __device__ __forceinline__ void xcd_barrier(const XcdBarrier& b) {
;     asm volatile("s_waitcnt vmcnt(0)" ::: "memory");
;     __syncthreads();
;     if (threadIdx.x == 0) {
;         unsigned* bar = b.bar;
;         __builtin_amdgcn_s_waitcnt(0);
;         unsigned nloc = b.st[0], nx = b.st[1];
;         if (nloc == 0u) { xcd_barrier_complete(bar, b.x, nloc, nx); b.st[0] = nloc; b.st[1] = nx; }
;         const unsigned old = xb_add(&bar[XB_XSUB(b.x)], 1u);
;         const unsigned gen = old / nloc;
;         if (old + 1u == (gen + 1u) * nloc) {
;             __builtin_amdgcn_fence(__ATOMIC_RELEASE, "agent");
;             asm volatile("s_waitcnt vmcnt(0)" ::: "memory");
;             const unsigned og = xb_add(&bar[XB_TOP], 1u);
;             const unsigned tg = og / nx;
;             if (og + 1u == (tg + 1u) * nx) xb_add(&bar[XB_TOPGEN], 1u);
;             else XB_SPIN(xb_ld(&bar[XB_TOPGEN]) == tg, bar);
.LBB0_934:
	s_cmp_lt_i32 s56, 9
	s_cselect_b64 s[4:5], -1, 0
	s_cmp_gt_i32 s57, 8
	s_cselect_b64 s[0:1], -1, 0
	s_and_b64 s[0:1], s[4:5], s[0:1]
	s_andn2_b64 vcc, exec, s[0:1]
	s_cbranch_vccnz .LBB0_1079
	s_andn2_b64 vcc, exec, s[6:7]
	s_cbranch_vccnz .LBB0_989
	s_getreg_b32 s3, hwreg(HW_REG_XCC_ID, 0, 4)
	s_waitcnt vmcnt(0)
	v_cmp_eq_u32_e32 vcc, 0, v178
	s_waitcnt vmcnt(0) lgkmcnt(0)
	s_barrier
	s_and_saveexec_b64 s[0:1], vcc
	s_cbranch_execz .LBB0_988
	buffer_inv sc1
	v_mov_b32_e32 v0, 0x23ff0
	ds_read2_b32 v[0:1], v0 offset1:1
	s_and_b32 s98, s3, 15
	s_lshl_b32 s98, s98, 8
	s_add_u32 s98, s54, s98
	s_addc_u32 s99, s55, 0
	s_add_u32 s98, s98, 0x22a3400
	s_addc_u32 s99, s99, 0
	v_mov_b32_e32 v2, 0
	v_mov_b32_e32 v3, 1
	global_atomic_add v4, v2, v3, s[98:99] sc0
	s_add_u32 s100, s54, 0x22a5400
	s_addc_u32 s101, s55, 0
	s_waitcnt vmcnt(0) lgkmcnt(0)
	v_mul_u32_u24_e32 v0, 7, v0
	v_mul_u32_u24_e32 v1, 7, v1
	v_add_u32_e32 v4, 1, v4
	v_cmp_eq_u32_e32 vcc, v4, v0
	s_cbranch_vccz .Lxb_nl_s6
	buffer_wbl2 sc1
	s_waitcnt vmcnt(0)
	global_atomic_add v2, v3, s[100:101]
	s_branch .Lxb_poll_s6

; __device__ __forceinline__ unsigned xb_ld(unsigned* p)              { return __hip_atomic_load(p, __ATOMIC_RELAXED, __HIP_MEMORY_SCOPE_AGENT); }
; __device__ __forceinline__ unsigned xb_add(unsigned* p, unsigned v) { return __hip_atomic_fetch_add(p, v, __ATOMIC_RELAXED, __HIP_MEMORY_SCOPE_AGENT); }
; #define XB_SPIN(cond, bar) do { unsigned _sp = 0; while (cond) { __builtin_amdgcn_s_sleep(1); \
;     if ((++_sp & 255u) == 0u) { if (xb_ld(&(bar)[XB_TMO])) break; if (_sp > XB_SPIN_CAP) { atomicAdd(&(bar)[XB_TMO], 1u); break; } } } } while (0)
; __device__ __forceinline__ void xcd_barrier(const XcdBarrier& b) {
;     asm volatile("s_waitcnt vmcnt(0)" ::: "memory");
;     __syncthreads();
;     if (threadIdx.x == 0) {
;         unsigned* bar = b.bar;
;         __builtin_amdgcn_s_waitcnt(0);
;         unsigned nloc = b.st[0], nx = b.st[1];
;         if (nloc == 0u) { xcd_barrier_complete(bar, b.x, nloc, nx); b.st[0] = nloc; b.st[1] = nx; }
;         const unsigned old = xb_add(&bar[XB_XSUB(b.x)], 1u);
;         const unsigned gen = old / nloc;
;         if (old + 1u == (gen + 1u) * nloc) {
;             __builtin_amdgcn_fence(__ATOMIC_RELEASE, "agent");
;             asm volatile("s_waitcnt vmcnt(0)" ::: "memory");
;             const unsigned og = xb_add(&bar[XB_TOP], 1u);
;             const unsigned tg = og / nx;
;             if (og + 1u == (tg + 1u) * nx) xb_add(&bar[XB_TOPGEN], 1u);
;             else XB_SPIN(xb_ld(&bar[XB_TOPGEN]) == tg, bar);
.LBB0_1079:
	s_cmp_lt_i32 s56, 10
	s_cselect_b64 s[6:7], -1, 0
	s_cmp_gt_i32 s57, 9
	s_cselect_b64 s[0:1], -1, 0
	s_and_b64 s[0:1], s[6:7], s[0:1]
	s_andn2_b64 vcc, exec, s[0:1]
	s_cbranch_vccnz .LBB0_1139
	s_andn2_b64 vcc, exec, s[4:5]
	s_cbranch_vccnz .LBB0_1134
	s_getreg_b32 s3, hwreg(HW_REG_XCC_ID, 0, 4)
	s_waitcnt vmcnt(0)
	v_cmp_eq_u32_e32 vcc, 0, v178
	s_waitcnt vmcnt(0) lgkmcnt(0)
	s_barrier
	s_and_saveexec_b64 s[0:1], vcc
	s_cbranch_execz .LBB0_1133
	buffer_inv sc1
	v_mov_b32_e32 v0, 0x23ff0
	ds_read2_b32 v[0:1], v0 offset1:1
	s_and_b32 s98, s3, 15
	s_lshl_b32 s98, s98, 8
	s_add_u32 s98, s54, s98
	s_addc_u32 s99, s55, 0
	s_add_u32 s98, s98, 0x22a3400
	s_addc_u32 s99, s99, 0
	v_mov_b32_e32 v2, 0
	v_mov_b32_e32 v3, 1
	global_atomic_add v4, v2, v3, s[98:99] sc0
	s_add_u32 s100, s54, 0x22a5400
	s_addc_u32 s101, s55, 0
	s_waitcnt vmcnt(0) lgkmcnt(0)
	v_mul_u32_u24_e32 v0, 8, v0
	v_mul_u32_u24_e32 v1, 8, v1
	v_add_u32_e32 v4, 1, v4
	v_cmp_eq_u32_e32 vcc, v4, v0
	s_cbranch_vccz .Lxb_nl_s7
	buffer_wbl2 sc1
	s_waitcnt vmcnt(0)
	global_atomic_add v2, v3, s[100:101]
	s_branch .Lxb_poll_s7

; __device__ __forceinline__ unsigned xb_ld(unsigned* p)              { return __hip_atomic_load(p, __ATOMIC_RELAXED, __HIP_MEMORY_SCOPE_AGENT); }
; __device__ __forceinline__ unsigned xb_add(unsigned* p, unsigned v) { return __hip_atomic_fetch_add(p, v, __ATOMIC_RELAXED, __HIP_MEMORY_SCOPE_AGENT); }
; #define XB_SPIN(cond, bar) do { unsigned _sp = 0; while (cond) { __builtin_amdgcn_s_sleep(1); \
;     if ((++_sp & 255u) == 0u) { if (xb_ld(&(bar)[XB_TMO])) break; if (_sp > XB_SPIN_CAP) { atomicAdd(&(bar)[XB_TMO], 1u); break; } } } } while (0)
; __device__ __forceinline__ void xcd_barrier(const XcdBarrier& b) {
;     asm volatile("s_waitcnt vmcnt(0)" ::: "memory");
;     __syncthreads();
;     if (threadIdx.x == 0) {
;         unsigned* bar = b.bar;
;         __builtin_amdgcn_s_waitcnt(0);
;         unsigned nloc = b.st[0], nx = b.st[1];
;         if (nloc == 0u) { xcd_barrier_complete(bar, b.x, nloc, nx); b.st[0] = nloc; b.st[1] = nx; }
;         const unsigned old = xb_add(&bar[XB_XSUB(b.x)], 1u);
;         const unsigned gen = old / nloc;
;         if (old + 1u == (gen + 1u) * nloc) {
;             __builtin_amdgcn_fence(__ATOMIC_RELEASE, "agent");
;             asm volatile("s_waitcnt vmcnt(0)" ::: "memory");
;             const unsigned og = xb_add(&bar[XB_TOP], 1u);
;             const unsigned tg = og / nx;
;             if (og + 1u == (tg + 1u) * nx) xb_add(&bar[XB_TOPGEN], 1u);
;             else XB_SPIN(xb_ld(&bar[XB_TOPGEN]) == tg, bar);
.LBB0_1139:
	s_cmp_lt_i32 s56, 11
	s_cselect_b64 s[4:5], -1, 0
	s_cmp_gt_i32 s57, 10
	s_cselect_b64 s[0:1], -1, 0
	s_and_b64 s[0:1], s[4:5], s[0:1]
	s_andn2_b64 vcc, exec, s[0:1]
	s_cbranch_vccnz .LBB0_1210
	s_andn2_b64 vcc, exec, s[6:7]
	s_cbranch_vccnz .LBB0_1194
	s_getreg_b32 s3, hwreg(HW_REG_XCC_ID, 0, 4)
	s_waitcnt vmcnt(0)
	v_cmp_eq_u32_e32 vcc, 0, v178
	s_waitcnt vmcnt(0) lgkmcnt(0)
	s_barrier
	s_and_saveexec_b64 s[0:1], vcc
	s_cbranch_execz .LBB0_1193
	buffer_inv sc1
	v_mov_b32_e32 v0, 0x23ff0
	ds_read2_b32 v[0:1], v0 offset1:1
	s_and_b32 s98, s3, 15
	s_lshl_b32 s98, s98, 8
	s_add_u32 s98, s54, s98
	s_addc_u32 s99, s55, 0
	s_add_u32 s98, s98, 0x22a3400
	s_addc_u32 s99, s99, 0
	v_mov_b32_e32 v2, 0
	v_mov_b32_e32 v3, 1
	global_atomic_add v4, v2, v3, s[98:99] sc0
	s_add_u32 s100, s54, 0x22a5400
	s_addc_u32 s101, s55, 0
	s_waitcnt vmcnt(0) lgkmcnt(0)
	v_mul_u32_u24_e32 v0, 9, v0
	v_mul_u32_u24_e32 v1, 9, v1
	v_add_u32_e32 v4, 1, v4
	v_cmp_eq_u32_e32 vcc, v4, v0
	s_cbranch_vccz .Lxb_nl_s8
	buffer_wbl2 sc1
	s_waitcnt vmcnt(0)
	global_atomic_add v2, v3, s[100:101]
	s_branch .Lxb_poll_s8

; __device__ __forceinline__ unsigned xb_ld(unsigned* p)              { return __hip_atomic_load(p, __ATOMIC_RELAXED, __HIP_MEMORY_SCOPE_AGENT); }
; __device__ __forceinline__ unsigned xb_add(unsigned* p, unsigned v) { return __hip_atomic_fetch_add(p, v, __ATOMIC_RELAXED, __HIP_MEMORY_SCOPE_AGENT); }
; #define XB_SPIN(cond, bar) do { unsigned _sp = 0; while (cond) { __builtin_amdgcn_s_sleep(1); \
;     if ((++_sp & 255u) == 0u) { if (xb_ld(&(bar)[XB_TMO])) break; if (_sp > XB_SPIN_CAP) { atomicAdd(&(bar)[XB_TMO], 1u); break; } } } } while (0)
; __device__ __forceinline__ void xcd_barrier(const XcdBarrier& b) {
;     asm volatile("s_waitcnt vmcnt(0)" ::: "memory");
;     __syncthreads();
;     if (threadIdx.x == 0) {
;         unsigned* bar = b.bar;
;         __builtin_amdgcn_s_waitcnt(0);
;         unsigned nloc = b.st[0], nx = b.st[1];
;         if (nloc == 0u) { xcd_barrier_complete(bar, b.x, nloc, nx); b.st[0] = nloc; b.st[1] = nx; }
;         const unsigned old = xb_add(&bar[XB_XSUB(b.x)], 1u);
;         const unsigned gen = old / nloc;
;         if (old + 1u == (gen + 1u) * nloc) {
;             __builtin_amdgcn_fence(__ATOMIC_RELEASE, "agent");
;             asm volatile("s_waitcnt vmcnt(0)" ::: "memory");
;             const unsigned og = xb_add(&bar[XB_TOP], 1u);
;             const unsigned tg = og / nx;
;             if (og + 1u == (tg + 1u) * nx) xb_add(&bar[XB_TOPGEN], 1u);
;             else XB_SPIN(xb_ld(&bar[XB_TOPGEN]) == tg, bar);
.LBB0_1210:
	s_cmp_lt_i32 s56, 12
	s_cselect_b64 s[10:11], -1, 0
	s_cmp_gt_i32 s57, 11
	s_cselect_b64 s[0:1], -1, 0
	s_and_b64 s[0:1], s[10:11], s[0:1]
	s_andn2_b64 vcc, exec, s[0:1]
	s_cbranch_vccnz .LBB0_1307
	s_andn2_b64 vcc, exec, s[4:5]
	s_cbranch_vccnz .LBB0_1265
	s_getreg_b32 s3, hwreg(HW_REG_XCC_ID, 0, 4)
	s_waitcnt vmcnt(0)
	v_cmp_eq_u32_e32 vcc, 0, v178
	s_waitcnt vmcnt(0) lgkmcnt(0)
	s_barrier
	s_and_saveexec_b64 s[0:1], vcc
	s_cbranch_execz .LBB0_1264
	buffer_inv sc1
	v_mov_b32_e32 v0, 0x23ff0
	ds_read2_b32 v[0:1], v0 offset1:1
	s_and_b32 s98, s3, 15
	s_lshl_b32 s98, s98, 8
	s_add_u32 s98, s54, s98
	s_addc_u32 s99, s55, 0
	s_add_u32 s98, s98, 0x22a3400
	s_addc_u32 s99, s99, 0
	v_mov_b32_e32 v2, 0
	v_mov_b32_e32 v3, 1
	global_atomic_add v4, v2, v3, s[98:99] sc0
	s_add_u32 s100, s54, 0x22a5400
	s_addc_u32 s101, s55, 0
	s_waitcnt vmcnt(0) lgkmcnt(0)
	v_mul_u32_u24_e32 v0, 10, v0
	v_mul_u32_u24_e32 v1, 10, v1
	v_add_u32_e32 v4, 1, v4
	v_cmp_eq_u32_e32 vcc, v4, v0
	s_cbranch_vccz .Lxb_nl_s9
	buffer_wbl2 sc1
	s_waitcnt vmcnt(0)
	global_atomic_add v2, v3, s[100:101]
	s_branch .Lxb_poll_s9

; __device__ __forceinline__ unsigned xb_ld(unsigned* p)              { return __hip_atomic_load(p, __ATOMIC_RELAXED, __HIP_MEMORY_SCOPE_AGENT); }
; __device__ __forceinline__ unsigned xb_add(unsigned* p, unsigned v) { return __hip_atomic_fetch_add(p, v, __ATOMIC_RELAXED, __HIP_MEMORY_SCOPE_AGENT); }
; #define XB_SPIN(cond, bar) do { unsigned _sp = 0; while (cond) { __builtin_amdgcn_s_sleep(1); \
;     if ((++_sp & 255u) == 0u) { if (xb_ld(&(bar)[XB_TMO])) break; if (_sp > XB_SPIN_CAP) { atomicAdd(&(bar)[XB_TMO], 1u); break; } } } } while (0)
; __device__ __forceinline__ void xcd_barrier(const XcdBarrier& b) {
;     asm volatile("s_waitcnt vmcnt(0)" ::: "memory");
;     __syncthreads();
;     if (threadIdx.x == 0) {
;         unsigned* bar = b.bar;
;         __builtin_amdgcn_s_waitcnt(0);
;         unsigned nloc = b.st[0], nx = b.st[1];
;         if (nloc == 0u) { xcd_barrier_complete(bar, b.x, nloc, nx); b.st[0] = nloc; b.st[1] = nx; }
;         const unsigned old = xb_add(&bar[XB_XSUB(b.x)], 1u);
;         const unsigned gen = old / nloc;
;         if (old + 1u == (gen + 1u) * nloc) {
;             __builtin_amdgcn_fence(__ATOMIC_RELEASE, "agent");
;             asm volatile("s_waitcnt vmcnt(0)" ::: "memory");
;             const unsigned og = xb_add(&bar[XB_TOP], 1u);
;             const unsigned tg = og / nx;
;             if (og + 1u == (tg + 1u) * nx) xb_add(&bar[XB_TOPGEN], 1u);
;             else XB_SPIN(xb_ld(&bar[XB_TOPGEN]) == tg, bar);
.LBB0_1307:
	s_cmp_lt_i32 s56, 13
	s_cselect_b64 s[6:7], -1, 0
	s_cmp_gt_i32 s57, 12
	s_cselect_b64 s[0:1], -1, 0
	s_and_b64 s[0:1], s[6:7], s[0:1]
	s_andn2_b64 vcc, exec, s[0:1]
	s_cbranch_vccnz .LBB0_1460
	s_andn2_b64 vcc, exec, s[10:11]
	s_cbranch_vccnz .LBB0_1362
	s_getreg_b32 s3, hwreg(HW_REG_XCC_ID, 0, 4)
	s_waitcnt vmcnt(0)
	v_cmp_eq_u32_e32 vcc, 0, v178
	s_waitcnt vmcnt(0) lgkmcnt(0)
	s_barrier
	s_and_saveexec_b64 s[0:1], vcc
	s_cbranch_execz .LBB0_1361
	buffer_inv sc1
	v_mov_b32_e32 v0, 0x23ff0
	ds_read2_b32 v[0:1], v0 offset1:1
	s_and_b32 s98, s3, 15
	s_lshl_b32 s98, s98, 8
	s_add_u32 s98, s54, s98
	s_addc_u32 s99, s55, 0
	s_add_u32 s98, s98, 0x22a3400
	s_addc_u32 s99, s99, 0
	v_mov_b32_e32 v2, 0
	v_mov_b32_e32 v3, 1
	global_atomic_add v4, v2, v3, s[98:99] sc0
	s_add_u32 s100, s54, 0x22a5400
	s_addc_u32 s101, s55, 0
	s_waitcnt vmcnt(0) lgkmcnt(0)
	v_mul_u32_u24_e32 v0, 11, v0
	v_mul_u32_u24_e32 v1, 11, v1
	v_add_u32_e32 v4, 1, v4
	v_cmp_eq_u32_e32 vcc, v4, v0
	s_cbranch_vccz .Lxb_nl_s10
	buffer_wbl2 sc1
	s_waitcnt vmcnt(0)
	global_atomic_add v2, v3, s[100:101]
	s_branch .Lxb_poll_s10

; __device__ __forceinline__ unsigned xb_ld(unsigned* p)              { return __hip_atomic_load(p, __ATOMIC_RELAXED, __HIP_MEMORY_SCOPE_AGENT); }
; __device__ __forceinline__ unsigned xb_add(unsigned* p, unsigned v) { return __hip_atomic_fetch_add(p, v, __ATOMIC_RELAXED, __HIP_MEMORY_SCOPE_AGENT); }
; #define XB_SPIN(cond, bar) do { unsigned _sp = 0; while (cond) { __builtin_amdgcn_s_sleep(1); \
;     if ((++_sp & 255u) == 0u) { if (xb_ld(&(bar)[XB_TMO])) break; if (_sp > XB_SPIN_CAP) { atomicAdd(&(bar)[XB_TMO], 1u); break; } } } } while (0)
; __device__ __forceinline__ void xcd_barrier(const XcdBarrier& b) {
;     asm volatile("s_waitcnt vmcnt(0)" ::: "memory");
;     __syncthreads();
;     if (threadIdx.x == 0) {
;         unsigned* bar = b.bar;
;         __builtin_amdgcn_s_waitcnt(0);
;         unsigned nloc = b.st[0], nx = b.st[1];
;         if (nloc == 0u) { xcd_barrier_complete(bar, b.x, nloc, nx); b.st[0] = nloc; b.st[1] = nx; }
;         const unsigned old = xb_add(&bar[XB_XSUB(b.x)], 1u);
;         const unsigned gen = old / nloc;
;         if (old + 1u == (gen + 1u) * nloc) {
;             __builtin_amdgcn_fence(__ATOMIC_RELEASE, "agent");
;             asm volatile("s_waitcnt vmcnt(0)" ::: "memory");
;             const unsigned og = xb_add(&bar[XB_TOP], 1u);
;             const unsigned tg = og / nx;
;             if (og + 1u == (tg + 1u) * nx) xb_add(&bar[XB_TOPGEN], 1u);
;             else XB_SPIN(xb_ld(&bar[XB_TOPGEN]) == tg, bar);
.Lsk_nowb:
.LBB0_1460:
	s_cmp_lt_i32 s56, 14
	s_cselect_b64 s[0:1], -1, 0
	s_cmp_gt_i32 s57, 13
	s_cselect_b64 s[4:5], -1, 0
	s_and_b64 s[0:1], s[0:1], s[4:5]
	s_andn2_b64 vcc, exec, s[0:1]
	s_cbranch_vccnz .LBB0_1520
	s_andn2_b64 vcc, exec, s[6:7]
	s_cbranch_vccnz .LBB0_1515
	s_getreg_b32 s3, hwreg(HW_REG_XCC_ID, 0, 4)
	s_waitcnt vmcnt(0)
	v_cmp_eq_u32_e32 vcc, 0, v178
	s_waitcnt vmcnt(0) lgkmcnt(0)
	s_barrier
	s_and_saveexec_b64 s[0:1], vcc
	s_cbranch_execz .LBB0_1514
	buffer_inv sc1
	v_mov_b32_e32 v0, 0x23ff0
	ds_read2_b32 v[0:1], v0 offset1:1
	s_and_b32 s98, s3, 15
	s_lshl_b32 s98, s98, 8
	s_add_u32 s98, s54, s98
	s_addc_u32 s99, s55, 0
	s_add_u32 s98, s98, 0x22a3400
	s_addc_u32 s99, s99, 0
	v_mov_b32_e32 v2, 0
	v_mov_b32_e32 v3, 1
	global_atomic_add v4, v2, v3, s[98:99] sc0
	s_add_u32 s100, s54, 0x22a5400
	s_addc_u32 s101, s55, 0
	s_waitcnt vmcnt(0) lgkmcnt(0)
	v_mul_u32_u24_e32 v0, 12, v0
	v_mul_u32_u24_e32 v1, 12, v1
	v_add_u32_e32 v4, 1, v4
	v_cmp_eq_u32_e32 vcc, v4, v0
	s_cbranch_vccz .Lxb_nl_s11
	buffer_wbl2 sc1
	s_waitcnt vmcnt(0)
	global_atomic_add v2, v3, s[100:101]
	s_branch .Lxb_poll_s11
